# hgrn_pass1 MFMA sections (scores, output product, state update): LDS fragment reads batched behind counted lgkmcnt instead of one lgkmcnt(0) per MFMA
# baseline (speedup 1.0000x reference)
; #define LAS __attribute__((address_space(3)))
; __device__ __forceinline__ void hgrn_pass1(const Frame& F, unsigned char* ws) {
;     ...
;             { const f32x4 eb = *(const LAS f32x4*)(VEC + 16 * w + 4 * lq);
; #pragma unroll
;               for (int vt = 0; vt < 8; ++vt) { S[vt] = S[vt] * eb;
;                   *(LAS v2u*)(L + H_ST + (16 * vt + li) * LDQ + (16 * w + 4 * lq) * 2) = (v2u){pk2(S[vt][0], S[vt][1]), pk2(S[vt][2], S[vt][3])}; } }
;             { const int ti = w >> 1;
; #pragma unroll
;               for (int q2 = 0; q2 < 2; ++q2) { const int si = 2 * (w & 1) + q2; f32x4 acc = {0.f, 0.f, 0.f, 0.f};
;                   if (si <= ti) {
; #pragma unroll
;                       for (int ks = 0; ks < 4; ++ks) acc = mfma16(*(const LAS bf16x8*)(L + H_KT + (16 * si + li) * LDQ + (32 * ks + 8 * lq) * 2), *(const LAS bf16x8*)(L + H_QT + (16 * ti + li) * LDQ + (32 * ks + 8 * lq) * 2), acc);
;                       if (si == ti) {
; #pragma unroll
;                           for (int r = 0; r < 4; ++r) if (4 * lq + r > li) acc[r] = 0.f; } }
;                   *(LAS v2u*)(L + H_P + (16 * ti + li) * LD64 + (16 * si + 4 * lq) * 2) = (v2u){pk2(acc[0], acc[1]), pk2(acc[2], acc[3])}; } }
;             __syncthreads();
;             { const int ti = w & 3, vt0 = 4 * (w >> 2), nps = (ti >> 1) + 1;
;               bf16x8 qf[4], pf[2];
; #pragma unroll
;               for (int ks = 0; ks < 4; ++ks) qf[ks] = *(const LAS bf16x8*)(L + H_QT + (16 * ti + li) * LDQ + (32 * ks + 8 * lq) * 2);
; #pragma unroll
;               for (int ks = 0; ks < 2; ++ks) pf[ks] = *(const LAS bf16x8*)(L + H_P + (16 * ti + li) * LD64 + (32 * ks + 8 * lq) * 2);
;               bf16* orow = PB + (size_t)(row_base + c * 64 + 16 * ti + li) * 2560 + 1024 + h * 128 + 4 * lq;
; #pragma unroll
;               for (int j = 0; j < 4; ++j) { const int vrow = 16 * (vt0 + j) + li; f32x4 acc = {0.f, 0.f, 0.f, 0.f};
; #pragma unroll
;                   for (int ks = 0; ks < 4; ++ks) acc = mfma16(*(const LAS bf16x8*)(L + H_ST + vrow * LDQ + (32 * ks + 8 * lq) * 2), qf[ks], acc);
;                   acc = mfma16(*(const LAS bf16x8*)(L + H_VTT + vrow * LD64 + (8 * lq) * 2), pf[0], acc);
;                   if (nps > 1) acc = mfma16(*(const LAS bf16x8*)(L + H_VTT + vrow * LD64 + (32 + 8 * lq) * 2), pf[1], acc);
.LBB0_689:
	s_or_b64 exec, exec, s[10:11]
	s_waitcnt lgkmcnt(0)
	s_barrier
	ds_read_b128 v[2:5], v98
	s_andn2_b64 vcc, exec, s[42:43]
	s_waitcnt lgkmcnt(0)
	v_pk_mul_f32 v[32:33], v[32:33], v[4:5]
	v_pk_mul_f32 v[30:31], v[30:31], v[2:3]
	v_cvt_pk_bf16_f32 v7, v32, v33
	v_cvt_pk_bf16_f32 v6, v30, v31
	v_pk_mul_f32 v[28:29], v[28:29], v[4:5]
	v_pk_mul_f32 v[26:27], v[26:27], v[2:3]
	ds_write_b64 v106, v[6:7]
	v_cvt_pk_bf16_f32 v6, v26, v27
	v_cvt_pk_bf16_f32 v7, v28, v29
	v_pk_mul_f32 v[24:25], v[24:25], v[4:5]
	v_pk_mul_f32 v[22:23], v[22:23], v[2:3]
	ds_write_b64 v106, v[6:7] offset:4352
	v_cvt_pk_bf16_f32 v6, v22, v23
	v_cvt_pk_bf16_f32 v7, v24, v25
	v_pk_mul_f32 v[20:21], v[20:21], v[4:5]
	v_pk_mul_f32 v[18:19], v[18:19], v[2:3]
	ds_write_b64 v106, v[6:7] offset:8704
	v_cvt_pk_bf16_f32 v6, v18, v19
	v_cvt_pk_bf16_f32 v7, v20, v21
	v_pk_mul_f32 v[16:17], v[16:17], v[4:5]
	v_pk_mul_f32 v[14:15], v[14:15], v[2:3]
	ds_write_b64 v106, v[6:7] offset:13056
	v_cvt_pk_bf16_f32 v6, v14, v15
	v_cvt_pk_bf16_f32 v7, v16, v17
	v_pk_mul_f32 v[12:13], v[12:13], v[4:5]
	v_pk_mul_f32 v[10:11], v[10:11], v[2:3]
	ds_write_b64 v106, v[6:7] offset:17408
	v_cvt_pk_bf16_f32 v6, v10, v11
	v_cvt_pk_bf16_f32 v7, v12, v13
	ds_write_b64 v106, v[6:7] offset:21760
	v_pk_mul_f32 v[8:9], v[48:49], v[4:5]
	v_pk_mul_f32 v[6:7], v[46:47], v[2:3]
	v_pk_mul_f32 v[4:5], v[36:37], v[4:5]
	v_pk_mul_f32 v[2:3], v[34:35], v[2:3]
	v_cvt_pk_bf16_f32 v38, v6, v7
	v_cvt_pk_bf16_f32 v39, v8, v9
	v_cvt_pk_bf16_f32 v34, v2, v3
	v_cvt_pk_bf16_f32 v35, v4, v5
	ds_write_b64 v106, v[38:39] offset:26112
	ds_write_b64 v106, v[34:35] offset:30464
	v_mov_b32_e32 v34, 0
	v_mov_b32_e32 v36, 0
	v_mov_b32_e32 v37, 0
	v_mov_b32_e32 v38, 0
	v_mov_b32_e32 v39, 0
	s_cbranch_vccnz .LBB0_692
	ds_read_b128 v[40:43], v107 offset:17408
	ds_read_b128 v[44:47], v118
	ds_read_b128 v[228:231], v107 offset:17472
	ds_read_b128 v[232:235], v118 offset:64
	ds_read_b128 v[236:239], v107 offset:17536
	ds_read_b128 v[240:243], v118 offset:128
	ds_read_b128 v[244:247], v107 offset:17600
	ds_read_b128 v[176:179], v118 offset:192
	s_andn2_b64 vcc, exec, s[90:91]
	s_waitcnt lgkmcnt(6)
	v_mfma_f32_16x16x32_bf16 v[36:39], v[40:43], v[44:47], 0
	s_waitcnt lgkmcnt(4)
	v_mfma_f32_16x16x32_bf16 v[36:39], v[228:231], v[232:235], v[36:39]
	s_waitcnt lgkmcnt(2)
	v_mfma_f32_16x16x32_bf16 v[36:39], v[236:239], v[240:243], v[36:39]
	s_waitcnt lgkmcnt(0)
	v_mfma_f32_16x16x32_bf16 v[36:39], v[244:247], v[176:179], v[36:39]
	s_cbranch_vccnz .LBB0_692
	v_mov_b32_e32 v40, s3
	s_nop 5
	v_cndmask_b32_e64 v35, v36, v40, s[20:21]
	v_cndmask_b32_e64 v37, 0, v37, s[22:23]
	v_cndmask_b32_e64 v36, v35, v36, s[22:23]
	v_cndmask_b32_e64 v38, v38, 0, s[24:25]
	v_cndmask_b32_e64 v39, v39, 0, s[26:27]
.LBB0_692:
	s_nop 6
	v_cvt_pk_bf16_f32 v36, v36, v37
	v_cvt_pk_bf16_f32 v37, v38, v39
	v_add_u32_e32 v35, s33, v99
	ds_write_b64 v35, v[36:37]
	s_andn2_b64 vcc, exec, s[50:51]
	v_mov_b32_e32 v35, 0
	v_mov_b32_e32 v36, 0
	v_mov_b32_e32 v37, 0
	s_cbranch_vccnz .LBB0_695
	ds_read_b128 v[38:41], v108 offset:17408
	ds_read_b128 v[42:45], v118
	ds_read_b128 v[228:231], v108 offset:17472
	ds_read_b128 v[232:235], v118 offset:64
	ds_read_b128 v[236:239], v108 offset:17536
	ds_read_b128 v[240:243], v118 offset:128
	ds_read_b128 v[244:247], v108 offset:17600
	ds_read_b128 v[176:179], v118 offset:192
	v_readlane_b32 s0, v252, 0
	v_readlane_b32 s1, v252, 1
	s_andn2_b64 vcc, exec, s[0:1]
	s_waitcnt lgkmcnt(6)
	v_mfma_f32_16x16x32_bf16 v[34:37], v[38:41], v[42:45], 0
	s_waitcnt lgkmcnt(4)
	v_mfma_f32_16x16x32_bf16 v[34:37], v[228:231], v[232:235], v[34:37]
	s_waitcnt lgkmcnt(2)
	v_mfma_f32_16x16x32_bf16 v[34:37], v[236:239], v[240:243], v[34:37]
	s_waitcnt lgkmcnt(0)
	v_mfma_f32_16x16x32_bf16 v[34:37], v[244:247], v[176:179], v[34:37]
	s_cbranch_vccnz .LBB0_695
	v_mov_b32_e32 v38, s3
	s_nop 5
	v_cndmask_b32_e64 v38, v34, v38, s[20:21]
	v_cndmask_b32_e64 v35, 0, v35, s[22:23]
	v_cndmask_b32_e64 v34, v38, v34, s[22:23]
	v_cndmask_b32_e64 v36, v36, 0, s[24:25]
	v_cndmask_b32_e64 v37, v37, 0, s[26:27]
.LBB0_695:
	s_nop 6
	v_cvt_pk_bf16_f32 v34, v34, v35
	v_cvt_pk_bf16_f32 v35, v36, v37
	v_add_u32_e32 v36, s9, v99
	ds_write_b64 v36, v[34:35]
	s_waitcnt lgkmcnt(0)
	s_barrier
	ds_read_b128 v[54:57], v109
	ds_read_b128 v[50:53], v109 offset:64
	ds_read_b128 v[46:49], v109 offset:128
	ds_read_b128 v[42:45], v109 offset:192
	ds_read_b128 v[38:41], v110
	ds_read_b128 v[34:37], v110 offset:64
	ds_read_b128 v[228:231], v111
	ds_read_b128 v[232:235], v111 offset:64
	ds_read_b128 v[236:239], v111 offset:128
	ds_read_b128 v[240:243], v111 offset:192
	ds_read_b128 v[244:247], v119 offset:53248
	ds_read_b128 v[176:179], v119 offset:53312
	s_andn2_b64 vcc, exec, s[36:37]
	s_waitcnt lgkmcnt(5)
	v_mfma_f32_16x16x32_bf16 v[58:61], v[228:231], v[54:57], 0
	s_waitcnt lgkmcnt(4)
	v_mfma_f32_16x16x32_bf16 v[58:61], v[232:235], v[50:53], v[58:61]
	s_waitcnt lgkmcnt(3)
	v_mfma_f32_16x16x32_bf16 v[58:61], v[236:239], v[46:49], v[58:61]
	s_waitcnt lgkmcnt(2)
	v_mfma_f32_16x16x32_bf16 v[58:61], v[240:243], v[42:45], v[58:61]
	s_waitcnt lgkmcnt(1)
	v_mfma_f32_16x16x32_bf16 v[58:61], v[244:247], v[38:41], v[58:61]
	v_cndmask_b32_e64 v90, 0, 1, s[36:37]
	v_cmp_ne_u32_e64 s[28:29], 1, v90
	s_cbranch_vccnz .LBB0_697
	s_waitcnt lgkmcnt(0)
	v_mfma_f32_16x16x32_bf16 v[58:61], v[176:179], v[34:37], v[58:61]
; #define LAS __attribute__((address_space(3)))
; __device__ __forceinline__ unsigned pk2(float lo, float hi) { const f32x2_cv v = {lo, hi}; const bf16x2_cv b = __builtin_convertvector(v, bf16x2_cv); return __builtin_bit_cast(unsigned, b); }
; __device__ __forceinline__ f32x4 mfma16(bf16x8 a, bf16x8 b, f32x4 c) { return __builtin_amdgcn_mfma_f32_16x16x32_bf16(a, b, c, 0, 0, 0); }
; __device__ __forceinline__ void hgrn_pass1(const Frame& F, unsigned char* ws) {
;     ...
;               bf16* orow = PB + (size_t)(row_base + c * 64 + 16 * ti + li) * 2560 + 1024 + h * 128 + 4 * lq;
; #pragma unroll
;               for (int j = 0; j < 4; ++j) { const int vrow = 16 * (vt0 + j) + li; f32x4 acc = {0.f, 0.f, 0.f, 0.f};
; #pragma unroll
;                   for (int ks = 0; ks < 4; ++ks) acc = mfma16(*(const LAS bf16x8*)(L + H_ST + vrow * LDQ + (32 * ks + 8 * lq) * 2), qf[ks], acc);
;                   acc = mfma16(*(const LAS bf16x8*)(L + H_VTT + vrow * LD64 + (8 * lq) * 2), pf[0], acc);
;                   if (nps > 1) acc = mfma16(*(const LAS bf16x8*)(L + H_VTT + vrow * LD64 + (32 + 8 * lq) * 2), pf[1], acc);
;                   *(v2u*)(orow + 16 * (vt0 + j)) = (v2u){pk2(acc[0], acc[1]), pk2(acc[2], acc[3])}; } }
.LBB0_697:
	v_add_u32_e32 v90, s31, v123
	v_mad_i64_i32 v[90:91], s[0:1], v90, s97, v[88:89]
	s_lshl_b32 s2, s4, 1
	s_nop 4
	v_cvt_pk_bf16_f32 v58, v58, v59
	v_cvt_pk_bf16_f32 v59, v60, v61
	v_lshl_add_u64 v[92:93], v[90:91], 0, s[2:3]
	global_store_dwordx2 v[92:93], v[58:59], off offset:2048
	ds_read_b128 v[228:231], v112
	ds_read_b128 v[232:235], v112 offset:64
	ds_read_b128 v[236:239], v112 offset:128
	ds_read_b128 v[240:243], v112 offset:192
	ds_read_b128 v[244:247], v120 offset:53248
	ds_read_b128 v[176:179], v120 offset:53312
	s_and_b64 vcc, exec, s[28:29]
	s_waitcnt lgkmcnt(5)
	v_mfma_f32_16x16x32_bf16 v[58:61], v[228:231], v[54:57], 0
	s_waitcnt lgkmcnt(4)
	v_mfma_f32_16x16x32_bf16 v[58:61], v[232:235], v[50:53], v[58:61]
	s_waitcnt lgkmcnt(3)
	v_mfma_f32_16x16x32_bf16 v[58:61], v[236:239], v[46:49], v[58:61]
	s_waitcnt lgkmcnt(2)
	v_mfma_f32_16x16x32_bf16 v[58:61], v[240:243], v[42:45], v[58:61]
	s_waitcnt lgkmcnt(1)
	v_mfma_f32_16x16x32_bf16 v[58:61], v[244:247], v[38:41], v[58:61]
	s_cbranch_vccnz .LBB0_699
	s_waitcnt lgkmcnt(0)
	v_mfma_f32_16x16x32_bf16 v[58:61], v[176:179], v[34:37], v[58:61]
.LBB0_699:
	s_nop 7
	v_cvt_pk_bf16_f32 v58, v58, v59
	v_cvt_pk_bf16_f32 v59, v60, v61
	global_store_dwordx2 v[92:93], v[58:59], off offset:2080
	ds_read_b128 v[228:231], v113
	ds_read_b128 v[232:235], v113 offset:64
	ds_read_b128 v[236:239], v113 offset:128
	ds_read_b128 v[240:243], v113 offset:192
	ds_read_b128 v[244:247], v121 offset:53248
	ds_read_b128 v[176:179], v121 offset:53312
	s_and_b64 vcc, exec, s[28:29]
	s_waitcnt lgkmcnt(5)
	v_mfma_f32_16x16x32_bf16 v[58:61], v[228:231], v[54:57], 0
	s_waitcnt lgkmcnt(4)
	v_mfma_f32_16x16x32_bf16 v[58:61], v[232:235], v[50:53], v[58:61]
	s_waitcnt lgkmcnt(3)
	v_mfma_f32_16x16x32_bf16 v[58:61], v[236:239], v[46:49], v[58:61]
	s_waitcnt lgkmcnt(2)
	v_mfma_f32_16x16x32_bf16 v[58:61], v[240:243], v[42:45], v[58:61]
	s_waitcnt lgkmcnt(1)
	v_mfma_f32_16x16x32_bf16 v[58:61], v[244:247], v[38:41], v[58:61]
	s_cbranch_vccnz .LBB0_701
	s_waitcnt lgkmcnt(0)
	v_mfma_f32_16x16x32_bf16 v[58:61], v[176:179], v[34:37], v[58:61]
.LBB0_701:
	s_nop 7
	v_cvt_pk_bf16_f32 v58, v58, v59
	v_cvt_pk_bf16_f32 v59, v60, v61
	global_store_dwordx2 v[92:93], v[58:59], off offset:2112
	ds_read_b128 v[228:231], v114
	ds_read_b128 v[232:235], v114 offset:64
	ds_read_b128 v[236:239], v114 offset:128
	ds_read_b128 v[240:243], v114 offset:192
	ds_read_b128 v[244:247], v122 offset:53248
	ds_read_b128 v[176:179], v122 offset:53312
	s_and_b64 vcc, exec, s[28:29]
	s_waitcnt lgkmcnt(5)
	v_mfma_f32_16x16x32_bf16 v[58:61], v[228:231], v[54:57], 0
	s_waitcnt lgkmcnt(4)
	v_mfma_f32_16x16x32_bf16 v[58:61], v[232:235], v[50:53], v[58:61]
	s_waitcnt lgkmcnt(3)
	v_mfma_f32_16x16x32_bf16 v[58:61], v[236:239], v[46:49], v[58:61]
	s_waitcnt lgkmcnt(2)
	v_mfma_f32_16x16x32_bf16 v[58:61], v[240:243], v[42:45], v[58:61]
	s_waitcnt lgkmcnt(1)
	v_mfma_f32_16x16x32_bf16 v[58:61], v[244:247], v[38:41], v[58:61]
	s_cbranch_vccnz .LBB0_703
	s_waitcnt lgkmcnt(0)
	v_mfma_f32_16x16x32_bf16 v[58:61], v[176:179], v[34:37], v[58:61]
; #define LAS __attribute__((address_space(3)))
; __device__ __forceinline__ unsigned pk2(float lo, float hi) { const f32x2_cv v = {lo, hi}; const bf16x2_cv b = __builtin_convertvector(v, bf16x2_cv); return __builtin_bit_cast(unsigned, b); }
; __device__ __forceinline__ f32x4 mfma16(bf16x8 a, bf16x8 b, f32x4 c) { return __builtin_amdgcn_mfma_f32_16x16x32_bf16(a, b, c, 0, 0, 0); }
; __device__ __forceinline__ void hgrn_pass1(const Frame& F, unsigned char* ws) {
;     ...
;                   *(v2u*)(orow + 16 * (vt0 + j)) = (v2u){pk2(acc[0], acc[1]), pk2(acc[2], acc[3])}; } }
;             { bf16x8 kf[2];
; #pragma unroll
;               for (int ks = 0; ks < 2; ++ks) kf[ks] = *(const LAS bf16x8*)(L + H_KTT + (16 * w + li) * LD64 + (32 * ks + 8 * lq) * 2);
;               const f32x4 cf = *(const LAS f32x4*)(VEC + 128 + 16 * w + 4 * lq);
; #pragma unroll
;               for (int vt = 0; vt < 8; ++vt) {
; #pragma unroll
;                   for (int ks = 0; ks < 2; ++ks) S[vt] = mfma16(kf[ks], *(const LAS bf16x8*)(L + H_VTT + (16 * vt + li) * LD64 + (32 * ks + 8 * lq) * 2), S[vt]);
;                   S[vt] = S[vt] * cf; } }
;         }
;         float* SF = (float*)(ws + WS_TMP + TMP_SF) + (size_t)unit * 16384;
; #pragma unroll
;         for (int vt = 0; vt < 8; ++vt)
; #pragma unroll
;             for (int r = 0; r < 4; ++r) SF[(16 * w + 4 * lq + r) * 128 + 16 * vt + li] = S[vt][r];
;         if (qd == 0) ((float*)(ws + WS_TMP + TMP_DS))[unit * 128 + k] = __expf(Bprev);
.LBB0_703:
	s_lshl_b32 s2, s5, 1
	s_nop 6
	v_cvt_pk_bf16_f32 v34, v58, v59
	v_cvt_pk_bf16_f32 v35, v60, v61
	v_lshl_add_u64 v[36:37], v[90:91], 0, s[2:3]
	global_store_dwordx2 v[36:37], v[34:35], off offset:2048
	ds_read_b128 v[42:45], v115 offset:34816
	ds_read_b128 v[38:41], v115 offset:34880
	ds_read_b128 v[34:37], v100
	ds_read_b128 v[46:49], v116 offset:53248
	ds_read_b128 v[228:231], v116 offset:53312
	ds_read_b128 v[232:235], v116 offset:55552
	ds_read_b128 v[236:239], v116 offset:55616
	ds_read_b128 v[240:243], v116 offset:57856
	ds_read_b128 v[244:247], v116 offset:57920
	ds_read_b128 v[176:179], v116 offset:60160
	s_add_i32 s31, s31, 64
	v_add_f32_e32 v125, v125, v174
	s_waitcnt lgkmcnt(6)
	v_mfma_f32_16x16x32_bf16 v[30:33], v[42:45], v[46:49], v[30:33]
	ds_read_b128 v[46:49], v116 offset:60224
	s_waitcnt lgkmcnt(6)
	v_mfma_f32_16x16x32_bf16 v[30:33], v[38:41], v[228:231], v[30:33]
	ds_read_b128 v[228:231], v116 offset:62464
	s_waitcnt lgkmcnt(6)
	v_mfma_f32_16x16x32_bf16 v[26:29], v[42:45], v[232:235], v[26:29]
	ds_read_b128 v[232:235], v116 offset:62528
	s_waitcnt lgkmcnt(6)
	v_mfma_f32_16x16x32_bf16 v[26:29], v[38:41], v[236:239], v[26:29]
	ds_read_b128 v[236:239], v116 offset:64768
	s_waitcnt lgkmcnt(6)
	v_mfma_f32_16x16x32_bf16 v[22:25], v[42:45], v[240:243], v[22:25]
	ds_read_b128 v[240:243], v116 offset:64832
	s_waitcnt lgkmcnt(6)
	v_mfma_f32_16x16x32_bf16 v[22:25], v[38:41], v[244:247], v[22:25]
	ds_read_b128 v[244:247], v117 offset:62464
	s_waitcnt lgkmcnt(6)
	v_mfma_f32_16x16x32_bf16 v[18:21], v[42:45], v[176:179], v[18:21]
	ds_read_b128 v[176:179], v117 offset:62528
	s_waitcnt lgkmcnt(6)
	v_mfma_f32_16x16x32_bf16 v[18:21], v[38:41], v[46:49], v[18:21]
	ds_read_b128 v[46:49], v117 offset:64768
	s_waitcnt lgkmcnt(6)
	v_mfma_f32_16x16x32_bf16 v[14:17], v[42:45], v[228:231], v[14:17]
	ds_read_b128 v[228:231], v117 offset:64832
	s_waitcnt lgkmcnt(6)
	v_mfma_f32_16x16x32_bf16 v[14:17], v[38:41], v[232:235], v[14:17]
	s_waitcnt lgkmcnt(5)
	v_mfma_f32_16x16x32_bf16 v[10:13], v[42:45], v[236:239], v[10:13]
	s_waitcnt lgkmcnt(4)
	v_mfma_f32_16x16x32_bf16 v[10:13], v[38:41], v[240:243], v[10:13]
	s_waitcnt lgkmcnt(3)
	v_mfma_f32_16x16x32_bf16 v[6:9], v[42:45], v[244:247], v[6:9]
	s_waitcnt lgkmcnt(2)
	v_mfma_f32_16x16x32_bf16 v[6:9], v[38:41], v[176:179], v[6:9]
	s_waitcnt lgkmcnt(1)
	v_mfma_f32_16x16x32_bf16 v[2:5], v[42:45], v[46:49], v[2:5]
	s_waitcnt lgkmcnt(0)
	v_mfma_f32_16x16x32_bf16 v[2:5], v[38:41], v[228:231], v[2:5]
	s_waitcnt lgkmcnt(0)
	s_nop 1
	v_pk_mul_f32 v[32:33], v[36:37], v[32:33]
	v_pk_mul_f32 v[30:31], v[34:35], v[30:31]
	v_pk_mul_f32 v[28:29], v[36:37], v[28:29]
	v_pk_mul_f32 v[26:27], v[34:35], v[26:27]
	v_pk_mul_f32 v[24:25], v[36:37], v[24:25]
	v_pk_mul_f32 v[22:23], v[34:35], v[22:23]
	v_pk_mul_f32 v[20:21], v[36:37], v[20:21]
	v_pk_mul_f32 v[18:19], v[34:35], v[18:19]
	v_pk_mul_f32 v[16:17], v[36:37], v[16:17]
	v_pk_mul_f32 v[14:15], v[34:35], v[14:15]
	v_pk_mul_f32 v[12:13], v[36:37], v[12:13]
	v_pk_mul_f32 v[10:11], v[34:35], v[10:11]
	v_pk_mul_f32 v[48:49], v[36:37], v[8:9]
	v_pk_mul_f32 v[46:47], v[34:35], v[6:7]
	v_pk_mul_f32 v[36:37], v[36:37], v[4:5]
	v_pk_mul_f32 v[34:35], v[34:35], v[2:3]
	s_cmpk_eq_i32 s31, 0x100
	s_cbranch_scc0 .LBB0_685
	s_ashr_i32 s31, s30, 31
	s_lshl_b64 s[0:1], s[30:31], 16
	v_readlane_b32 s10, v251, 56
	v_readlane_b32 s11, v251, 57
	s_add_u32 s0, s10, s0
	s_addc_u32 s1, s11, s1
	v_lshl_add_u64 v[2:3], v[68:69], 2, s[0:1]
	global_store_dword v[2:3], v30, off
	v_lshl_add_u64 v[2:3], v[66:67], 2, s[0:1]
	v_lshl_add_u64 v[4:5], v[72:73], 2, s[0:1]
	global_store_dword v[2:3], v31, off offset:512
	global_store_dword v[2:3], v32, off offset:1024
	global_store_dword v[2:3], v33, off offset:1536
	global_store_dword v[2:3], v26, off offset:64
	global_store_dword v[4:5], v27, off offset:512
	global_store_dword v[4:5], v28, off offset:1024
	global_store_dword v[4:5], v29, off offset:1536
	global_store_dword v[2:3], v22, off offset:128
	v_lshl_add_u64 v[4:5], v[74:75], 2, s[0:1]
	global_store_dword v[4:5], v23, off offset:512
	global_store_dword v[4:5], v24, off offset:1024
	global_store_dword v[4:5], v25, off offset:1536
	global_store_dword v[2:3], v18, off offset:192
	v_lshl_add_u64 v[4:5], v[76:77], 2, s[0:1]
	global_store_dword v[4:5], v19, off offset:512
	global_store_dword v[4:5], v20, off offset:1024
	global_store_dword v[4:5], v21, off offset:1536
	global_store_dword v[2:3], v14, off offset:256
	v_lshl_add_u64 v[4:5], v[78:79], 2, s[0:1]
	global_store_dword v[4:5], v15, off offset:512
	global_store_dword v[4:5], v16, off offset:1024
	global_store_dword v[4:5], v17, off offset:1536
	global_store_dword v[2:3], v10, off offset:320
	v_lshl_add_u64 v[4:5], v[80:81], 2, s[0:1]
	global_store_dword v[4:5], v11, off offset:512
	global_store_dword v[4:5], v12, off offset:1024
	global_store_dword v[4:5], v13, off offset:1536
	global_store_dword v[2:3], v46, off offset:384
	v_lshl_add_u64 v[4:5], v[82:83], 2, s[0:1]
	global_store_dword v[4:5], v47, off offset:512
	global_store_dword v[4:5], v48, off offset:1024
	global_store_dword v[4:5], v49, off offset:1536
	global_store_dword v[2:3], v34, off offset:448
	v_lshl_add_u64 v[2:3], v[84:85], 2, s[0:1]
	global_store_dword v[2:3], v35, off offset:512
	global_store_dword v[2:3], v36, off offset:1024
	global_store_dword v[2:3], v37, off offset:1536
	s_and_saveexec_b64 s[10:11], s[18:19]
	s_cbranch_execz .LBB0_683
	v_mul_f32_e32 v2, 0x3fb8aa3b, v125
	v_exp_f32_e32 v4, v2
	v_lshl_or_b32 v2, s30, 7, v62
	v_readlane_b32 s0, v251, 58
	v_ashrrev_i32_e32 v3, 31, v2
	v_readlane_b32 s1, v251, 59
	s_nop 1
	v_lshl_add_u64 v[2:3], v[2:3], 2, s[0:1]
	global_store_dword v[2:3], v4, off
	s_branch .LBB0_683
